# attn k-loop software pipelined: S(k+1) MFMAs inside step k exp/PV phase, K tiles two steps ahead; permlane32_swap row-max exchange
# speedup vs baseline: 1.0062x; 1.0062x over previous
.Lfa_btab_skip:
	s_lshl_b32 s40, s8, 6
	s_lshl_b64 s[0:1], s[50:51], 16
	s_add_u32 s0, s73, s0
	s_addc_u32 s1, s19, s1
	s_lshl_b32 s2, s8, 7
	s_add_u32 s0, s0, s2
	s_addc_u32 s1, s1, 0
	v_mov_b32_e32 v121, v32
	v_lshl_add_u64 v[0:1], s[0:1], 0, v[120:121]
	s_mov_b64 s[0:1], 0x200000
	v_lshlrev_b64 v[4:5], 1, v[114:115]
	v_lshl_add_u64 v[2:3], v[0:1], 0, s[0:1]
	v_lshl_add_u64 v[6:7], v[0:1], 0, v[4:5]
	v_lshl_add_u64 v[4:5], v[2:3], 0, v[4:5]
	global_load_dwordx4 v[16:19], v[6:7], off
	global_load_dwordx4 v[20:23], v[4:5], off
	v_lshl_add_u64 v[0:1], v[0:1], 0, v[118:119]
	global_load_dwordx4 v[24:27], v[0:1], off
	v_lshl_add_u64 v[0:1], v[2:3], 0, v[118:119]
	global_load_dwordx4 v[28:31], v[0:1], off
	s_lshl_b32 s2, s40, 1
	s_mul_i32 s0, s50, 0x600000
	s_mul_hi_i32 s1, s50, 0x600000
	s_add_u32 s0, s24, s0
	s_addc_u32 s1, s25, s1
	s_add_u32 s0, s0, s2
	s_addc_u32 s1, s1, 0
	v_lshl_add_u64 v[252:253], s[0:1], 0, v[112:113]
	v_lshl_add_u64 v[252:253], v[252:253], 0, v[120:121]
	global_load_dwordx4 v[236:239], v[252:253], off offset:1024
	global_load_dwordx4 v[240:243], v[252:253], off offset:1536
	s_movk_i32 s3, 0x800
	s_cmp_gt_i32 s45, 0
	s_cselect_b32 s2, 0x30400, s3
	s_mov_b32 s3, 0
	v_lshl_add_u64 v[248:249], v[252:253], 0, s[2:3]
	global_load_dwordx4 v[244:247], v[248:249], off
	v_mov_b32_e32 v33, v32
	s_cmp_gt_i32 s45, 15
	v_mov_b32_e32 v34, v32
	v_mov_b32_e32 v35, v32
	v_mov_b32_e32 v36, v32
	v_mov_b32_e32 v37, v32
	v_mov_b32_e32 v38, v32
	v_mov_b32_e32 v39, v32
	v_mov_b32_e32 v40, v32
	v_mov_b32_e32 v41, v32
	v_mov_b32_e32 v42, v32
	v_mov_b32_e32 v43, v32
	v_mov_b32_e32 v44, v32
	v_mov_b32_e32 v45, v32
	v_mov_b32_e32 v46, v32
	v_mov_b32_e32 v47, v32
	v_mov_b64_e32 v[0:1], v[32:33]
	s_cselect_b64 s[30:31], -1, 0
	s_cmp_lt_i32 s45, 16
	s_mov_b32 s3, 0
	v_subrev_u32_e32 v66, 31, v130
	v_mov_b32_e32 v67, 0
	v_mov_b32_e32 v48, 0xff800000
	s_mov_b64 s[34:35], -1
	v_mov_b64_e32 v[2:3], v[34:35]
	v_mov_b64_e32 v[4:5], v[36:37]
	v_mov_b64_e32 v[6:7], v[38:39]
	v_mov_b64_e32 v[8:9], v[40:41]
	v_mov_b64_e32 v[10:11], v[42:43]
	v_mov_b64_e32 v[12:13], v[44:45]
	v_mov_b64_e32 v[14:15], v[46:47]
	s_cselect_b64 s[0:1], -1, 0
	s_waitcnt vmcnt(6)
	ds_write_b128 v195, v[16:19]
	s_waitcnt vmcnt(4)
	ds_write_b128 v195, v[24:27] offset:9216
	ds_write_b128 v195, v[20:23] offset:18432
	s_waitcnt vmcnt(3)
	ds_write_b128 v195, v[28:31] offset:27648
	v_mov_b64_e32 v[16:17], v[32:33]
	v_mov_b64_e32 v[18:19], v[34:35]
	v_mov_b64_e32 v[20:21], v[36:37]
	v_mov_b64_e32 v[22:23], v[38:39]
	v_mov_b64_e32 v[24:25], v[40:41]
	v_mov_b64_e32 v[26:27], v[42:43]
	v_mov_b64_e32 v[28:29], v[44:45]
	v_mov_b64_e32 v[30:31], v[46:47]
	s_waitcnt lgkmcnt(0)
	s_barrier

.LBB0_1449:
	s_add_i32 s6, s45, 1
	s_max_i32 s2, s45, 8
	s_lshl_b32 s0, s6, 1
	s_sub_i32 s8, s0, s2
	s_mul_i32 s1, s50, 0x600000
	s_mul_hi_i32 s0, s50, 0x600000
	s_add_u32 s1, s24, s1
	s_addc_u32 s3, s25, s0
	s_lshl_b32 s0, s40, 1
	s_add_u32 s0, s1, s0
	s_addc_u32 s1, s3, 0
	v_lshl_add_u64 v[0:1], s[0:1], 0, v[112:113]
	v_mov_b32_e32 v121, v32
	v_lshl_add_u64 v[0:1], v[0:1], 0, v[120:121]
	s_waitcnt lgkmcnt(0)
	s_barrier
	ds_read_b32 v104, v194
	s_cmp_lt_i32 s8, -7
	s_waitcnt vmcnt(2)
	ds_write_b128 v195, v[236:239]
	s_waitcnt vmcnt(1)
	ds_write_b128 v195, v[240:243] offset:18432
	s_waitcnt vmcnt(0)
	ds_write_b128 v195, v[244:247] offset:9216
	s_waitcnt lgkmcnt(0)
	s_barrier
	s_cbranch_scc1 .LBB0_1268
	v_lshl_add_u64 v[132:133], s[0:1], 0, v[120:121]
	s_add_i32 s0, s2, -8
	s_not_b32 s1, s45
	s_add_i32 s7, s0, s1
	s_lshl_b32 s1, s45, 1
	v_mov_b32_e32 v46, v32
	v_mov_b32_e32 v47, v32
	s_sub_i32 s9, s1, s2
	v_mov_b32_e32 v33, v32
	v_mov_b32_e32 v34, v32
	v_mov_b32_e32 v35, v32
	v_mov_b32_e32 v36, v32
	v_mov_b32_e32 v37, v32
	v_mov_b32_e32 v38, v32
	v_mov_b32_e32 v39, v32
	v_mov_b32_e32 v40, v32
	v_mov_b32_e32 v41, v32
	v_mov_b32_e32 v42, v32
	v_mov_b32_e32 v43, v32
	v_mov_b32_e32 v44, v32
	v_mov_b32_e32 v45, v32
	v_mov_b64_e32 v[78:79], v[46:47]
	v_mov_b64_e32 v[62:63], v[46:47]
	v_sub_u32_e32 v117, v130, v152
	s_add_i32 s8, s8, 7
	s_add_i32 s9, s9, 10
	s_sub_i32 s28, s0, s45
	s_mov_b32 s2, 0
	v_mov_b32_e32 v121, 0
	v_mov_b32_e32 v123, 0xff800000
	v_mov_b64_e32 v[76:77], v[44:45]
	v_mov_b64_e32 v[74:75], v[42:43]
	v_mov_b64_e32 v[72:73], v[40:41]
	v_mov_b64_e32 v[70:71], v[38:39]
	v_mov_b64_e32 v[68:69], v[36:37]
	v_mov_b64_e32 v[66:67], v[34:35]
	v_mov_b64_e32 v[64:65], v[32:33]
	v_mov_b64_e32 v[60:61], v[44:45]
	v_mov_b64_e32 v[58:59], v[42:43]
	v_mov_b64_e32 v[56:57], v[40:41]
	v_mov_b64_e32 v[54:55], v[38:39]
	v_mov_b64_e32 v[52:53], v[36:37]
	v_mov_b64_e32 v[50:51], v[34:35]
	v_mov_b64_e32 v[48:49], v[32:33]
	v_add_u32_e32 v21, v156, v157
	v_add_u32_e32 v33, v156, v158
	ds_read_b128 v[134:137], v21
	ds_read_b128 v[138:141], v21 offset:32
	ds_read_b128 v[142:145], v21 offset:64
	ds_read_b128 v[146:149], v21 offset:96
	ds_read_b128 v[236:239], v33
	ds_read_b128 v[240:243], v33 offset:32
	ds_read_b128 v[244:247], v33 offset:64
	ds_read_b128 v[248:251], v33 offset:96
	s_waitcnt lgkmcnt(7)
	v_mfma_f32_32x32x16_bf16 v[0:15], v[134:137], v[80:83], 0
	s_waitcnt lgkmcnt(6)
	v_mfma_f32_32x32x16_bf16 v[0:15], v[138:141], v[84:87], v[0:15]
	s_waitcnt lgkmcnt(5)
	v_mfma_f32_32x32x16_bf16 v[0:15], v[142:145], v[88:91], v[0:15]
	s_waitcnt lgkmcnt(4)
	v_mfma_f32_32x32x16_bf16 v[0:15], v[146:149], v[92:95], v[0:15]
	s_waitcnt lgkmcnt(3)
	v_mfma_f32_32x32x16_bf16 v[16:31], v[236:239], v[80:83], 0
	s_waitcnt lgkmcnt(2)
	v_mfma_f32_32x32x16_bf16 v[16:31], v[240:243], v[84:87], v[16:31]
	s_waitcnt lgkmcnt(1)
	v_mfma_f32_32x32x16_bf16 v[16:31], v[244:247], v[88:91], v[16:31]
	s_waitcnt lgkmcnt(0)
	v_mfma_f32_32x32x16_bf16 v[16:31], v[248:251], v[92:95], v[16:31]
.LBB0_1451:
	s_add_i32 s29, s2, 1
	s_cmp_lt_i32 s2, s8
	s_cselect_b64 s[30:31], -1, 0
	s_cmp_ge_i32 s2, s8
	s_cbranch_scc1 .LBB0_1453
	s_add_i32 s0, s28, s2
	s_cmp_lt_i32 s2, s45
	s_cselect_b32 s0, s29, s0
	s_movk_i32 s1, 0x400
	v_lshl_add_u32 v252, s0, 6, v108
	s_cselect_b32 s40, s1, 0x800
	v_mad_i64_i32 v[252:253], s[0:1], v252, s68, v[132:133]
	v_lshl_add_u64 v[252:253], v[252:253], 0, s[40:41]
	global_load_dwordx4 v[100:103], v[252:253], off offset:512
	s_cmp_ge_i32 s29, s8
	s_cbranch_scc1 .LBB0_1453
	s_add_i32 s0, s28, s29
	s_add_i32 s1, s29, 1
	s_cmp_lt_i32 s29, s45
	s_cselect_b32 s0, s1, s0
	s_movk_i32 s1, 0x400
	s_cselect_b32 s40, s1, 0x800
	v_lshl_add_u32 v252, s0, 6, v108
	v_mad_i64_i32 v[252:253], s[0:1], v252, s68, v[132:133]
	v_lshl_add_u64 v[252:253], v[252:253], 0, s[40:41]
	global_load_dwordx4 v[96:99], v[252:253], off
.LBB0_1453:
	s_cmp_lg_u32 s6, s2
	s_cbranch_scc1 .LBB0_1455
	ds_bpermute_b32 v236, v155, v121
	v_mov_b32_e32 v46, v32
	v_mov_b32_e32 v47, v32
	v_mov_b32_e32 v33, v32
	v_mov_b32_e32 v34, v32
	s_waitcnt lgkmcnt(0)
	v_add_f32_e32 v236, v121, v236
	v_div_scale_f32 v237, s[0:1], v236, v236, v105
	v_rcp_f32_e32 v238, v237
	v_mov_b32_e32 v35, v32
	v_mov_b32_e32 v36, v32
	v_mov_b32_e32 v37, v32
	v_fma_f32 v239, -v237, v238, 1.0
	v_fmac_f32_e32 v238, v239, v238
	v_div_scale_f32 v239, vcc, v105, v236, v105
	v_mul_f32_e32 v240, v239, v238
	v_fma_f32 v241, -v237, v240, v239
	v_fmac_f32_e32 v240, v241, v238
	v_fma_f32 v237, -v237, v240, v239
	v_div_fmas_f32 v237, v237, v238, v240
	ds_read_b128 v[238:241], v210
	v_div_fixup_f32 v236, v237, v236, v105
	v_mov_b32_e32 v38, v32
	v_mov_b32_e32 v39, v32
	v_mov_b32_e32 v40, v32
	s_waitcnt lgkmcnt(0)
	v_pk_fma_f32 v[238:239], v[64:65], v[236:237], v[238:239] op_sel_hi:[1,0,1]
	v_pk_fma_f32 v[240:241], v[66:67], v[236:237], v[240:241] op_sel_hi:[1,0,1]
	ds_write_b128 v210, v[238:241]
	ds_read_b128 v[238:241], v210 offset:1024
	v_mov_b32_e32 v41, v32
	v_mov_b32_e32 v42, v32
	v_mov_b32_e32 v43, v32
	v_mov_b32_e32 v44, v32
	s_waitcnt lgkmcnt(0)
	v_pk_fma_f32 v[238:239], v[68:69], v[236:237], v[238:239] op_sel_hi:[1,0,1]
	v_pk_fma_f32 v[240:241], v[70:71], v[236:237], v[240:241] op_sel_hi:[1,0,1]
	ds_write_b128 v210, v[238:241] offset:1024
	ds_read_b128 v[238:241], v210 offset:2048
	v_mov_b32_e32 v45, v32
	v_mov_b32_e32 v121, 0
	v_mov_b32_e32 v123, 0xff800000
	s_waitcnt lgkmcnt(0)
	v_pk_fma_f32 v[238:239], v[72:73], v[236:237], v[238:239] op_sel_hi:[1,0,1]
	v_pk_fma_f32 v[240:241], v[74:75], v[236:237], v[240:241] op_sel_hi:[1,0,1]
	ds_write_b128 v210, v[238:241] offset:2048
	ds_read_b128 v[238:241], v210 offset:3072
	s_waitcnt lgkmcnt(0)
	v_pk_fma_f32 v[238:239], v[76:77], v[236:237], v[238:239] op_sel_hi:[1,0,1]
	v_pk_fma_f32 v[240:241], v[78:79], v[236:237], v[240:241] op_sel_hi:[1,0,1]
	ds_write_b128 v210, v[238:241] offset:3072
	ds_read_b128 v[238:241], v210 offset:4096
	v_mov_b64_e32 v[78:79], v[46:47]
	v_mov_b64_e32 v[76:77], v[44:45]
	v_mov_b64_e32 v[74:75], v[42:43]
	v_mov_b64_e32 v[72:73], v[40:41]
	s_waitcnt lgkmcnt(0)
	v_pk_fma_f32 v[238:239], v[48:49], v[236:237], v[238:239] op_sel_hi:[1,0,1]
	v_pk_fma_f32 v[240:241], v[50:51], v[236:237], v[240:241] op_sel_hi:[1,0,1]
	ds_write_b128 v210, v[238:241] offset:4096
	ds_read_b128 v[238:241], v210 offset:5120
	v_mov_b64_e32 v[70:71], v[38:39]
	v_mov_b64_e32 v[68:69], v[36:37]
	v_mov_b64_e32 v[66:67], v[34:35]
	v_mov_b64_e32 v[64:65], v[32:33]
	s_waitcnt lgkmcnt(0)
	v_pk_fma_f32 v[238:239], v[52:53], v[236:237], v[238:239] op_sel_hi:[1,0,1]
	v_pk_fma_f32 v[240:241], v[54:55], v[236:237], v[240:241] op_sel_hi:[1,0,1]
	ds_write_b128 v210, v[238:241] offset:5120
	ds_read_b128 v[238:241], v210 offset:6144
	s_waitcnt lgkmcnt(0)
	v_pk_fma_f32 v[238:239], v[56:57], v[236:237], v[238:239] op_sel_hi:[1,0,1]
	v_pk_fma_f32 v[240:241], v[58:59], v[236:237], v[240:241] op_sel_hi:[1,0,1]
	ds_write_b128 v210, v[238:241] offset:6144
	ds_read_b128 v[238:241], v210 offset:7168
	s_waitcnt lgkmcnt(0)
	v_pk_fma_f32 v[238:239], v[60:61], v[236:237], v[238:239] op_sel_hi:[1,0,1]
	v_pk_fma_f32 v[240:241], v[62:63], v[236:237], v[240:241] op_sel_hi:[1,0,1]
	v_mov_b64_e32 v[62:63], v[46:47]
	v_mov_b64_e32 v[60:61], v[44:45]
	v_mov_b64_e32 v[58:59], v[42:43]
	v_mov_b64_e32 v[56:57], v[40:41]
	v_mov_b64_e32 v[54:55], v[38:39]
	v_mov_b64_e32 v[52:53], v[36:37]
	v_mov_b64_e32 v[50:51], v[34:35]
	v_mov_b64_e32 v[48:49], v[32:33]
	ds_write_b128 v210, v[238:241] offset:7168
.LBB0_1455:
	s_and_b32 s36, s2, 1
	s_cmp_gt_i32 s2, s45
	s_cselect_b64 s[0:1], -1, 0
	s_and_b64 s[34:35], s[0:1], exec
	s_cselect_b32 s40, s7, 0
	s_add_i32 s40, s40, s2
	v_readfirstlane_b32 s3, v117
	s_lshl_b32 s50, s40, 6
	s_add_i32 s2, s3, 31
	s_cmp_lt_i32 s2, s50
	s_cbranch_scc1 .LBB0_1470
	s_sub_i32 s3, s3, s50
	s_sub_i32 s3, s3, 63
	s_cmpk_gt_i32 s3, 0x1ff
	s_cselect_b64 s[34:35], -1, 0
	s_and_b64 s[34:35], s[0:1], s[34:35]
	s_and_b64 vcc, exec, s[34:35]
	s_cbranch_vccnz .LBB0_1470
	s_mul_i32 s37, s36, 0x2400
	s_cmpk_gt_i32 s3, 0x70
	s_cselect_b64 s[34:35], -1, 0
	s_and_b64 s[52:53], s[0:1], s[34:35]
	s_sub_i32 s51, s2, s50
	s_cmpk_lt_i32 s51, 0x200
	s_cselect_b64 s[2:3], -1, 0
	v_cndmask_b32_e64 v33, 0, 1, s[34:35]
	v_cndmask_b32_e64 v34, 0, 1, s[2:3]
	s_and_b64 s[2:3], s[52:53], exec
	v_readfirstlane_b32 s2, v34
	v_readfirstlane_b32 s3, v33
	s_cselect_b32 s2, s2, s3
	s_bitcmp1_b32 s2, 0
	s_cselect_b64 s[34:35], -1, 0
	s_xor_b64 s[34:35], s[34:35], -1
	s_mov_b64 s[2:3], -1
	s_and_b64 vcc, exec, s[34:35]
	s_nop 1
	s_cbranch_vccz .Lfa_fast
	v_or_b32_e32 v125, s50, v153
	s_cmpk_lt_i32 s51, 0x110
	v_sub_u32_e32 v33, v130, v125
	s_cbranch_scc1 .LBB0_1460
	v_cmp_lt_i32_e32 vcc, s67, v33
	s_and_b64 vcc, s[0:1], vcc
	v_xad_u32 v36, v125, -1, v130
	v_cndmask_b32_e32 v35, 0, v211, vcc
	v_cmp_lt_i32_e32 vcc, s67, v36
	v_or_b32_e32 v38, 2, v125
	s_and_b64 vcc, s[0:1], vcc
	v_sub_u32_e32 v38, v130, v38
	v_med3_i32 v37, v36, -1, v209
	v_cndmask_b32_e32 v36, 0, v211, vcc
	v_med3_i32 v39, v38, -1, v209
	v_cmp_lt_i32_e32 vcc, s67, v38
	v_or_b32_e32 v38, 3, v125
	s_and_b64 vcc, s[0:1], vcc
	v_sub_u32_e32 v38, v130, v38
	v_cndmask_b32_e32 v40, 0, v211, vcc
	v_med3_i32 v41, v38, -1, v209
	v_cmp_lt_i32_e32 vcc, s67, v38
	v_or_b32_e32 v38, 8, v125
	s_and_b64 vcc, s[0:1], vcc
	v_sub_u32_e32 v38, v130, v38
	v_cndmask_b32_e32 v42, 0, v211, vcc
	v_med3_i32 v43, v38, -1, v209
	v_cmp_lt_i32_e32 vcc, s67, v38
	v_or_b32_e32 v38, 9, v125
	s_and_b64 vcc, s[0:1], vcc
	v_sub_u32_e32 v38, v130, v38
	v_cndmask_b32_e32 v44, 0, v211, vcc
	v_med3_i32 v45, v38, -1, v209
	v_cmp_lt_i32_e32 vcc, s67, v38
	v_or_b32_e32 v38, 10, v125
	s_and_b64 vcc, s[0:1], vcc
	v_sub_u32_e32 v38, v130, v38
	v_cndmask_b32_e32 v46, 0, v211, vcc
	v_med3_i32 v47, v38, -1, v209
	v_cmp_lt_i32_e32 vcc, s67, v38
	v_or_b32_e32 v38, 11, v125
	v_sub_u32_e32 v38, v130, v38
	v_med3_i32 v34, v33, -1, v209
	v_med3_i32 v127, v38, -1, v209
	v_lshl_add_u32 v34, v34, 2, s69
	v_lshl_add_u32 v37, v37, 2, s69
	v_lshl_add_u32 v41, v41, 2, s69
	v_lshl_add_u32 v43, v43, 2, s69
	v_lshl_add_u32 v45, v45, 2, s69
	v_lshl_add_u32 v47, v47, 2, s69
	v_lshl_add_u32 v127, v127, 2, s69
	v_lshl_add_u32 v39, v39, 2, s69
	ds_read_b32 v34, v34 offset:256
	ds_read_b32 v37, v37 offset:256
	ds_read_b32 v129, v39 offset:256
	ds_read_b32 v41, v41 offset:256
	ds_read_b32 v43, v43 offset:256
	ds_read_b32 v45, v45 offset:256
	ds_read_b32 v47, v47 offset:256
	ds_read_b32 v127, v127 offset:256
	s_and_b64 vcc, s[0:1], vcc
	v_cndmask_b32_e32 v131, 0, v211, vcc
	v_cmp_lt_i32_e32 vcc, s67, v38
	s_and_b64 vcc, s[0:1], vcc
	s_nop 0
	v_cndmask_b32_e32 v134, 0, v211, vcc
	s_waitcnt lgkmcnt(7)
	v_fmac_f32_e32 v34, 0x3fb8aa3b, v0
	s_waitcnt lgkmcnt(6)
	v_fmac_f32_e32 v37, 0x3fb8aa3b, v1
	v_add_f32_e32 v38, v35, v34
	v_add_f32_e32 v39, v36, v37
	s_waitcnt lgkmcnt(5)
	v_fmac_f32_e32 v129, 0x3fb8aa3b, v2
	s_waitcnt lgkmcnt(4)
	v_fmac_f32_e32 v41, 0x3fb8aa3b, v3
	v_max3_f32 v34, v38, s70, v39
	v_add_f32_e32 v36, v40, v129
	v_add_f32_e32 v37, v42, v41
	s_waitcnt lgkmcnt(3)
	v_fmac_f32_e32 v43, 0x3fb8aa3b, v4
	s_waitcnt lgkmcnt(2)
	v_fmac_f32_e32 v45, 0x3fb8aa3b, v5
	v_max3_f32 v34, v34, v36, v37
	v_add_f32_e32 v40, v44, v43
	v_add_f32_e32 v41, v46, v45
	s_waitcnt lgkmcnt(1)
	v_fmac_f32_e32 v47, 0x3fb8aa3b, v6
	s_waitcnt lgkmcnt(0)
	v_fmac_f32_e32 v127, 0x3fb8aa3b, v7
	v_max3_f32 v42, v34, v40, v41
	v_add_f32_e32 v34, v131, v47
	v_add_f32_e32 v35, v134, v127
	v_max3_f32 v42, v42, v34, v35
	v_or_b32_e32 v43, 16, v125
	v_sub_u32_e32 v43, v130, v43
	v_cmp_lt_i32_e32 vcc, s67, v43
	v_or_b32_e32 v45, 17, v125
	s_and_b64 vcc, s[0:1], vcc
	v_sub_u32_e32 v45, v130, v45
	v_med3_i32 v44, v43, -1, v209
	v_cndmask_b32_e32 v43, 0, v211, vcc
	v_cmp_lt_i32_e32 vcc, s67, v45
	v_or_b32_e32 v47, 18, v125
	s_and_b64 vcc, s[0:1], vcc
	v_sub_u32_e32 v47, v130, v47
	v_med3_i32 v46, v45, -1, v209
	v_cndmask_b32_e32 v45, 0, v211, vcc
	v_cmp_lt_i32_e32 vcc, s67, v47
	v_or_b32_e32 v129, 19, v125
	s_and_b64 vcc, s[0:1], vcc
	v_sub_u32_e32 v129, v130, v129
	v_med3_i32 v127, v47, -1, v209
	v_cndmask_b32_e32 v47, 0, v211, vcc
	v_cmp_lt_i32_e32 vcc, s67, v129
	v_or_b32_e32 v134, 24, v125
	s_and_b64 vcc, s[0:1], vcc
	v_sub_u32_e32 v134, v130, v134
	v_med3_i32 v131, v129, -1, v209
	v_cndmask_b32_e32 v129, 0, v211, vcc
	v_med3_i32 v135, v134, -1, v209
	v_cmp_lt_i32_e32 vcc, s67, v134
	v_or_b32_e32 v134, 25, v125
	s_and_b64 vcc, s[0:1], vcc
	v_sub_u32_e32 v134, v130, v134
	v_cndmask_b32_e32 v136, 0, v211, vcc
	v_med3_i32 v137, v134, -1, v209
	v_cmp_lt_i32_e32 vcc, s67, v134
	v_or_b32_e32 v134, 26, v125
	s_and_b64 vcc, s[0:1], vcc
	v_sub_u32_e32 v134, v130, v134
	v_cndmask_b32_e32 v138, 0, v211, vcc
	v_med3_i32 v139, v134, -1, v209
	v_cmp_lt_i32_e32 vcc, s67, v134
	v_or_b32_e32 v134, 27, v125
	v_sub_u32_e32 v134, v130, v134
	v_med3_i32 v140, v134, -1, v209
	v_lshl_add_u32 v44, v44, 2, s69
	v_lshl_add_u32 v46, v46, 2, s69
	v_lshl_add_u32 v127, v127, 2, s69
	v_lshl_add_u32 v131, v131, 2, s69
	v_lshl_add_u32 v137, v137, 2, s69
	v_lshl_add_u32 v139, v139, 2, s69
	v_lshl_add_u32 v140, v140, 2, s69
	v_lshl_add_u32 v135, v135, 2, s69
	ds_read_b32 v44, v44 offset:256
	ds_read_b32 v46, v46 offset:256
	ds_read_b32 v127, v127 offset:256
	ds_read_b32 v131, v131 offset:256
	ds_read_b32 v141, v135 offset:256
	ds_read_b32 v137, v137 offset:256
	ds_read_b32 v139, v139 offset:256
	ds_read_b32 v140, v140 offset:256
	s_and_b64 vcc, s[0:1], vcc
	v_cndmask_b32_e32 v142, 0, v211, vcc
	v_cmp_lt_i32_e32 vcc, s67, v134
	s_and_b64 vcc, s[0:1], vcc
	s_nop 0
	v_cndmask_b32_e32 v143, 0, v211, vcc
	s_waitcnt lgkmcnt(7)
	v_fmac_f32_e32 v44, 0x3fb8aa3b, v8
	s_waitcnt lgkmcnt(6)
	v_fmac_f32_e32 v46, 0x3fb8aa3b, v9
	v_add_f32_e32 v134, v43, v44
	v_add_f32_e32 v135, v45, v46
	s_waitcnt lgkmcnt(5)
	v_fmac_f32_e32 v127, 0x3fb8aa3b, v10
	s_waitcnt lgkmcnt(4)
	v_fmac_f32_e32 v131, 0x3fb8aa3b, v11
	v_max3_f32 v42, v42, v134, v135
	v_add_f32_e32 v44, v47, v127
	v_add_f32_e32 v45, v129, v131
	s_waitcnt lgkmcnt(3)
	v_fmac_f32_e32 v141, 0x3fb8aa3b, v12
	s_waitcnt lgkmcnt(2)
	v_fmac_f32_e32 v137, 0x3fb8aa3b, v13
	v_max3_f32 v42, v42, v44, v45
	v_add_f32_e32 v46, v136, v141
	v_add_f32_e32 v47, v138, v137
	s_waitcnt lgkmcnt(1)
	v_fmac_f32_e32 v139, 0x3fb8aa3b, v14
	s_waitcnt lgkmcnt(0)
	v_fmac_f32_e32 v140, 0x3fb8aa3b, v15
	v_max3_f32 v127, v42, v46, v47
	v_add_f32_e32 v42, v142, v139
	v_add_f32_e32 v43, v143, v140
	v_max3_f32 v127, v127, v42, v43
	v_or_b32_e32 v129, 32, v125
	v_sub_u32_e32 v129, v130, v129
	v_cmp_lt_i32_e32 vcc, s67, v129
	v_or_b32_e32 v136, 33, v125
	s_and_b64 vcc, s[0:1], vcc
	v_sub_u32_e32 v136, v130, v136
	v_med3_i32 v131, v129, -1, v209
	v_cndmask_b32_e32 v129, 0, v211, vcc
	v_cmp_lt_i32_e32 vcc, s67, v136
	v_or_b32_e32 v138, 34, v125
	s_and_b64 vcc, s[0:1], vcc
	v_sub_u32_e32 v138, v130, v138
	v_med3_i32 v137, v136, -1, v209
	v_cndmask_b32_e32 v136, 0, v211, vcc
	v_cmp_lt_i32_e32 vcc, s67, v138
	v_or_b32_e32 v140, 35, v125
	s_and_b64 vcc, s[0:1], vcc
	v_sub_u32_e32 v140, v130, v140
	v_med3_i32 v139, v138, -1, v209
	v_cndmask_b32_e32 v138, 0, v211, vcc
	v_cmp_lt_i32_e32 vcc, s67, v140
	v_or_b32_e32 v142, 40, v125
	s_and_b64 vcc, s[0:1], vcc
	v_sub_u32_e32 v142, v130, v142
	v_med3_i32 v141, v140, -1, v209
	v_cndmask_b32_e32 v140, 0, v211, vcc
	v_med3_i32 v143, v142, -1, v209
	v_cmp_lt_i32_e32 vcc, s67, v142
	v_or_b32_e32 v142, 41, v125
	s_and_b64 vcc, s[0:1], vcc
	v_sub_u32_e32 v142, v130, v142
	v_cndmask_b32_e32 v144, 0, v211, vcc
	v_med3_i32 v145, v142, -1, v209
	v_cmp_lt_i32_e32 vcc, s67, v142
	v_or_b32_e32 v142, 42, v125
	s_and_b64 vcc, s[0:1], vcc
	v_sub_u32_e32 v142, v130, v142
	v_cndmask_b32_e32 v146, 0, v211, vcc
	v_med3_i32 v147, v142, -1, v209
	v_cmp_lt_i32_e32 vcc, s67, v142
	v_or_b32_e32 v142, 43, v125
	v_sub_u32_e32 v142, v130, v142
	v_med3_i32 v148, v142, -1, v209
	v_lshl_add_u32 v131, v131, 2, s69
	v_lshl_add_u32 v137, v137, 2, s69
	v_lshl_add_u32 v139, v139, 2, s69
	v_lshl_add_u32 v141, v141, 2, s69
	v_lshl_add_u32 v145, v145, 2, s69
	v_lshl_add_u32 v147, v147, 2, s69
	v_lshl_add_u32 v148, v148, 2, s69
	v_lshl_add_u32 v143, v143, 2, s69
	ds_read_b32 v131, v131 offset:256
	ds_read_b32 v137, v137 offset:256
	ds_read_b32 v139, v139 offset:256
	ds_read_b32 v141, v141 offset:256
	ds_read_b32 v149, v143 offset:256
	ds_read_b32 v145, v145 offset:256
	ds_read_b32 v147, v147 offset:256
	ds_read_b32 v148, v148 offset:256
	s_and_b64 vcc, s[0:1], vcc
	v_cndmask_b32_e32 v150, 0, v211, vcc
	v_cmp_lt_i32_e32 vcc, s67, v142
	s_and_b64 vcc, s[0:1], vcc
	s_nop 0
	v_cndmask_b32_e32 v151, 0, v211, vcc
	s_waitcnt lgkmcnt(7)
	v_fmac_f32_e32 v131, 0x3fb8aa3b, v16
	s_waitcnt lgkmcnt(6)
	v_fmac_f32_e32 v137, 0x3fb8aa3b, v17
	v_add_f32_e32 v142, v129, v131
	v_add_f32_e32 v143, v136, v137
	s_waitcnt lgkmcnt(5)
	v_fmac_f32_e32 v139, 0x3fb8aa3b, v18
	s_waitcnt lgkmcnt(4)
	v_fmac_f32_e32 v141, 0x3fb8aa3b, v19
	v_max3_f32 v127, v127, v142, v143
	v_add_f32_e32 v138, v138, v139
	v_add_f32_e32 v139, v140, v141
	s_waitcnt lgkmcnt(3)
	v_fmac_f32_e32 v149, 0x3fb8aa3b, v20
	s_waitcnt lgkmcnt(2)
	v_fmac_f32_e32 v145, 0x3fb8aa3b, v21
	v_max3_f32 v127, v127, v138, v139
	v_add_f32_e32 v140, v144, v149
	v_add_f32_e32 v141, v146, v145
	s_waitcnt lgkmcnt(1)
	v_fmac_f32_e32 v147, 0x3fb8aa3b, v22
	s_waitcnt lgkmcnt(0)
	v_fmac_f32_e32 v148, 0x3fb8aa3b, v23
	v_max3_f32 v127, v127, v140, v141
	v_add_f32_e32 v136, v150, v147
	v_add_f32_e32 v137, v151, v148
	v_max3_f32 v127, v127, v136, v137
	v_or_b32_e32 v129, 48, v125
	v_sub_u32_e32 v129, v130, v129
	v_cmp_lt_i32_e32 vcc, s67, v129
	v_or_b32_e32 v144, 49, v125
	s_and_b64 vcc, s[0:1], vcc
	v_sub_u32_e32 v144, v130, v144
	v_med3_i32 v131, v129, -1, v209
	v_cndmask_b32_e32 v129, 0, v211, vcc
	v_cmp_lt_i32_e32 vcc, s67, v144
	v_or_b32_e32 v146, 50, v125
	s_and_b64 vcc, s[0:1], vcc
	v_sub_u32_e32 v146, v130, v146
	v_med3_i32 v145, v144, -1, v209
	v_cndmask_b32_e32 v144, 0, v211, vcc
	v_cmp_lt_i32_e32 vcc, s67, v146
	v_or_b32_e32 v148, 51, v125
	s_and_b64 vcc, s[0:1], vcc
	v_sub_u32_e32 v148, v130, v148
	v_med3_i32 v147, v146, -1, v209
	v_cndmask_b32_e32 v146, 0, v211, vcc
	v_cmp_lt_i32_e32 vcc, s67, v148
	v_or_b32_e32 v150, 56, v125
	s_and_b64 vcc, s[0:1], vcc
	v_sub_u32_e32 v150, v130, v150
	v_med3_i32 v149, v148, -1, v209
	v_cndmask_b32_e32 v148, 0, v211, vcc
	v_med3_i32 v151, v150, -1, v209
	v_cmp_lt_i32_e32 vcc, s67, v150
	v_or_b32_e32 v150, 57, v125
	s_and_b64 vcc, s[0:1], vcc
	v_sub_u32_e32 v150, v130, v150
	v_cndmask_b32_e32 v213, 0, v211, vcc
	v_med3_i32 v214, v150, -1, v209
	v_cmp_lt_i32_e32 vcc, s67, v150
	v_or_b32_e32 v150, 58, v125
	v_sub_u32_e32 v150, v130, v150
	v_or_b32_e32 v125, 59, v125
	s_and_b64 vcc, s[0:1], vcc
	v_med3_i32 v216, v150, -1, v209
	v_sub_u32_e32 v125, v130, v125
	v_lshl_add_u32 v131, v131, 2, s69
	v_lshl_add_u32 v145, v145, 2, s69
	v_lshl_add_u32 v147, v147, 2, s69
	v_lshl_add_u32 v149, v149, 2, s69
	v_lshl_add_u32 v214, v214, 2, s69
	v_cndmask_b32_e32 v215, 0, v211, vcc
	v_lshl_add_u32 v216, v216, 2, s69
	v_cmp_lt_i32_e32 vcc, s67, v150
	v_med3_i32 v150, v125, -1, v209
	v_lshl_add_u32 v151, v151, 2, s69
	v_lshl_add_u32 v150, v150, 2, s69
	ds_read_b32 v131, v131 offset:256
	ds_read_b32 v145, v145 offset:256
	ds_read_b32 v147, v147 offset:256
	ds_read_b32 v149, v149 offset:256
	ds_read_b32 v217, v151 offset:256
	ds_read_b32 v214, v214 offset:256
	ds_read_b32 v216, v216 offset:256
	ds_read_b32 v218, v150 offset:256
	s_and_b64 vcc, s[0:1], vcc
	v_cndmask_b32_e32 v219, 0, v211, vcc
	v_cmp_lt_i32_e32 vcc, s67, v125
	s_and_b64 vcc, s[0:1], vcc
	s_nop 0
	v_cndmask_b32_e32 v125, 0, v211, vcc
	s_waitcnt lgkmcnt(7)
	v_fmac_f32_e32 v131, 0x3fb8aa3b, v24
	s_waitcnt lgkmcnt(6)
	v_fmac_f32_e32 v145, 0x3fb8aa3b, v25
	v_add_f32_e32 v150, v129, v131
	v_add_f32_e32 v151, v144, v145
	s_waitcnt lgkmcnt(5)
	v_fmac_f32_e32 v147, 0x3fb8aa3b, v26
	s_waitcnt lgkmcnt(4)
	v_fmac_f32_e32 v149, 0x3fb8aa3b, v27
	v_max3_f32 v127, v127, v150, v151
	v_add_f32_e32 v146, v146, v147
	v_add_f32_e32 v147, v148, v149
	s_waitcnt lgkmcnt(3)
	v_fmac_f32_e32 v217, 0x3fb8aa3b, v28
	s_waitcnt lgkmcnt(2)
	v_fmac_f32_e32 v214, 0x3fb8aa3b, v29
	v_max3_f32 v127, v127, v146, v147
	v_add_f32_e32 v148, v213, v217
	v_add_f32_e32 v149, v215, v214
	s_waitcnt lgkmcnt(1)
	v_fmac_f32_e32 v216, 0x3fb8aa3b, v30
	s_waitcnt lgkmcnt(0)
	v_fmac_f32_e32 v218, 0x3fb8aa3b, v31
	v_max3_f32 v127, v127, v148, v149
	v_add_f32_e32 v144, v219, v216
	v_add_f32_e32 v145, v125, v218
	v_max3_f32 v129, v127, v144, v145
	s_mov_b64 s[2:3], 0

.Lfa_norescale2:
	v_exp_f32_e32 v0, v0
	v_exp_f32_e32 v1, v1
	v_add_f32_e32 v37, v0, v37
	v_exp_f32_e32 v2, v2
	v_add_f32_e32 v37, v1, v37
	v_exp_f32_e32 v3, v3
	v_add_f32_e32 v37, v2, v37
	v_exp_f32_e32 v4, v4
	v_add_f32_e32 v37, v3, v37
	v_exp_f32_e32 v5, v5
	v_add_f32_e32 v37, v4, v37
	v_exp_f32_e32 v6, v6
	v_add_f32_e32 v37, v5, v37
	v_exp_f32_e32 v7, v7
	v_add_f32_e32 v37, v6, v37
	s_nop 0
	v_add_f32_e32 v37, v7, v37
	v_cvt_pk_bf16_f32 v0, v0, v1
	v_cvt_pk_bf16_f32 v1, v2, v3
	v_cvt_pk_bf16_f32 v2, v4, v5
	v_cvt_pk_bf16_f32 v3, v6, v7
	s_waitcnt lgkmcnt(14)
	s_nop 0
	v_mfma_f32_32x32x16_bf16 v[64:79], v[236:239], v[0:3], v[64:79]
	s_waitcnt lgkmcnt(12)
	v_mfma_f32_32x32x16_bf16 v[48:63], v[240:243], v[0:3], v[48:63]
	v_exp_f32_e32 v8, v8
	v_exp_f32_e32 v9, v9
	v_add_f32_e32 v37, v8, v37
	v_exp_f32_e32 v10, v10
	v_add_f32_e32 v37, v9, v37
	v_exp_f32_e32 v11, v11
	v_add_f32_e32 v37, v10, v37
	v_exp_f32_e32 v12, v12
	v_add_f32_e32 v37, v11, v37
	v_exp_f32_e32 v13, v13
	v_add_f32_e32 v37, v12, v37
	v_exp_f32_e32 v14, v14
	v_add_f32_e32 v37, v13, v37
	v_exp_f32_e32 v15, v15
	v_add_f32_e32 v37, v14, v37
	s_nop 0
	v_add_f32_e32 v37, v15, v37
	v_cvt_pk_bf16_f32 v8, v8, v9
	v_cvt_pk_bf16_f32 v9, v10, v11
	v_cvt_pk_bf16_f32 v10, v12, v13
	v_cvt_pk_bf16_f32 v11, v14, v15
	s_waitcnt lgkmcnt(10)
	s_nop 0
	v_mfma_f32_32x32x16_bf16 v[64:79], v[244:247], v[8:11], v[64:79]
	s_waitcnt lgkmcnt(8)
	v_mfma_f32_32x32x16_bf16 v[48:63], v[248:251], v[8:11], v[48:63]
	s_waitcnt vmcnt(0)
	s_waitcnt lgkmcnt(0)
	v_add_u32_e32 v252, s37, v195
	ds_write_b128 v252, v[96:99]
	s_xor_b32 s2, s36, 3
	s_mulk_i32 s2, 0x2400
	v_add_u32_e32 v252, s2, v195
	ds_write_b128 v252, v[100:103]
	s_sub_i32 s3, 0x2400, s37
	v_add_u32_e32 v252, s3, v156
	v_add_u32_e32 v253, v252, v157
	v_add_u32_e32 v252, v252, v158
	ds_read_b128 v[236:239], v253
	ds_read_b128 v[240:243], v253 offset:32
	ds_read_b128 v[244:247], v253 offset:64
	ds_read_b128 v[248:251], v253 offset:96
	ds_read_b128 v[38:41], v252
	ds_read_b128 v[42:45], v252 offset:32
	v_exp_f32_e32 v16, v16
	v_exp_f32_e32 v17, v17
	v_add_f32_e32 v37, v16, v37
	s_waitcnt lgkmcnt(5)
	v_mfma_f32_32x32x16_bf16 v[0:15], v[236:239], v[80:83], 0
	v_exp_f32_e32 v18, v18
	v_add_f32_e32 v37, v17, v37
	v_exp_f32_e32 v19, v19
	v_add_f32_e32 v37, v18, v37
	v_exp_f32_e32 v20, v20
	v_add_f32_e32 v37, v19, v37
	v_exp_f32_e32 v21, v21
	v_add_f32_e32 v37, v20, v37
	s_waitcnt lgkmcnt(4)
	v_mfma_f32_32x32x16_bf16 v[0:15], v[240:243], v[84:87], v[0:15]
	v_exp_f32_e32 v22, v22
	v_add_f32_e32 v37, v21, v37
	v_exp_f32_e32 v23, v23
	v_add_f32_e32 v37, v22, v37
	s_nop 0
	v_add_f32_e32 v37, v23, v37
	v_cvt_pk_bf16_f32 v16, v16, v17
	v_cvt_pk_bf16_f32 v17, v18, v19
	v_cvt_pk_bf16_f32 v18, v20, v21
	v_cvt_pk_bf16_f32 v19, v22, v23
	s_nop 1
	v_mfma_f32_32x32x16_bf16 v[64:79], v[134:137], v[16:19], v[64:79]
	v_mfma_f32_32x32x16_bf16 v[48:63], v[138:141], v[16:19], v[48:63]
	ds_read_b128 v[96:99], v252 offset:64
	ds_read_b128 v[100:103], v252 offset:96
	v_exp_f32_e32 v24, v24
	v_exp_f32_e32 v25, v25
	v_add_f32_e32 v37, v24, v37
	s_waitcnt lgkmcnt(5)
	v_mfma_f32_32x32x16_bf16 v[0:15], v[244:247], v[88:91], v[0:15]
	v_exp_f32_e32 v26, v26
	v_add_f32_e32 v37, v25, v37
	v_exp_f32_e32 v27, v27
	v_add_f32_e32 v37, v26, v37
	v_exp_f32_e32 v28, v28
	v_add_f32_e32 v37, v27, v37
	v_exp_f32_e32 v29, v29
	v_add_f32_e32 v37, v28, v37
	s_waitcnt lgkmcnt(4)
	v_mfma_f32_32x32x16_bf16 v[0:15], v[248:251], v[92:95], v[0:15]
	v_exp_f32_e32 v30, v30
	v_add_f32_e32 v37, v29, v37
	v_exp_f32_e32 v31, v31
	v_add_f32_e32 v37, v30, v37
	s_nop 0
	v_add_f32_e32 v37, v31, v37
	v_cvt_pk_bf16_f32 v24, v24, v25
	v_cvt_pk_bf16_f32 v25, v26, v27
	v_cvt_pk_bf16_f32 v26, v28, v29
	v_cvt_pk_bf16_f32 v27, v30, v31
	s_nop 1
	v_mfma_f32_32x32x16_bf16 v[64:79], v[142:145], v[24:27], v[64:79]
	v_mfma_f32_32x32x16_bf16 v[48:63], v[146:149], v[24:27], v[48:63]
	s_waitcnt lgkmcnt(3)
	v_mfma_f32_32x32x16_bf16 v[16:31], v[38:41], v[80:83], 0
	s_waitcnt lgkmcnt(2)
	v_mfma_f32_32x32x16_bf16 v[16:31], v[42:45], v[84:87], v[16:31]
	v_fmac_f32_e32 v37, v121, v34
	v_mov_b32_e32 v123, v33
	v_mov_b32_e32 v121, v37
	s_waitcnt lgkmcnt(1)
	v_mfma_f32_32x32x16_bf16 v[16:31], v[96:99], v[88:91], v[16:31]
	s_waitcnt lgkmcnt(0)
	v_mfma_f32_32x32x16_bf16 v[16:31], v[100:103], v[92:95], v[16:31]
.LBB0_1470:
.LBB0_1472:
	s_cmp_eq_u32 s9, s29
	s_waitcnt lgkmcnt(0)
	s_barrier
	s_cbranch_scc1 .LBB0_1269
	s_mov_b32 s2, s29
	s_branch .LBB0_1451

.Lfa_norescale:
	v_fmamk_f32 v0, v0, 0x3fb8aa3b, v36
	v_fmamk_f32 v1, v1, 0x3fb8aa3b, v36
	v_fmamk_f32 v2, v2, 0x3fb8aa3b, v36
	v_fmamk_f32 v3, v3, 0x3fb8aa3b, v36
	v_fmamk_f32 v4, v4, 0x3fb8aa3b, v36
	v_fmamk_f32 v5, v5, 0x3fb8aa3b, v36
	v_fmamk_f32 v6, v6, 0x3fb8aa3b, v36
	v_fmamk_f32 v7, v7, 0x3fb8aa3b, v36
	v_fmamk_f32 v8, v8, 0x3fb8aa3b, v36
	v_fmamk_f32 v9, v9, 0x3fb8aa3b, v36
	v_fmamk_f32 v10, v10, 0x3fb8aa3b, v36
	v_fmamk_f32 v11, v11, 0x3fb8aa3b, v36
	v_fmamk_f32 v12, v12, 0x3fb8aa3b, v36
	v_fmamk_f32 v13, v13, 0x3fb8aa3b, v36
	v_fmamk_f32 v14, v14, 0x3fb8aa3b, v36
	v_fmamk_f32 v15, v15, 0x3fb8aa3b, v36
	v_fmamk_f32 v16, v16, 0x3fb8aa3b, v36
	v_fmamk_f32 v17, v17, 0x3fb8aa3b, v36
	v_fmamk_f32 v18, v18, 0x3fb8aa3b, v36
	v_fmamk_f32 v19, v19, 0x3fb8aa3b, v36
	v_fmamk_f32 v20, v20, 0x3fb8aa3b, v36
	v_fmamk_f32 v21, v21, 0x3fb8aa3b, v36
	v_fmamk_f32 v22, v22, 0x3fb8aa3b, v36
	v_fmamk_f32 v23, v23, 0x3fb8aa3b, v36
	v_fmamk_f32 v24, v24, 0x3fb8aa3b, v36
	v_fmamk_f32 v25, v25, 0x3fb8aa3b, v36
	v_fmamk_f32 v26, v26, 0x3fb8aa3b, v36
	v_fmamk_f32 v27, v27, 0x3fb8aa3b, v36
	v_fmamk_f32 v28, v28, 0x3fb8aa3b, v36
	v_fmamk_f32 v29, v29, 0x3fb8aa3b, v36
	v_fmamk_f32 v30, v30, 0x3fb8aa3b, v36
	v_fmamk_f32 v31, v31, 0x3fb8aa3b, v36
	v_exp_f32_e32 v0, v0
	v_exp_f32_e32 v1, v1
	v_add_f32_e32 v37, v0, v37
	v_exp_f32_e32 v2, v2
	v_add_f32_e32 v37, v1, v37
	v_exp_f32_e32 v3, v3
	v_add_f32_e32 v37, v2, v37
	v_exp_f32_e32 v4, v4
	v_add_f32_e32 v37, v3, v37
	v_exp_f32_e32 v5, v5
	v_add_f32_e32 v37, v4, v37
	v_exp_f32_e32 v6, v6
	v_add_f32_e32 v37, v5, v37
	v_exp_f32_e32 v7, v7
	v_add_f32_e32 v37, v6, v37
	s_nop 0
	v_add_f32_e32 v37, v7, v37
	v_cvt_pk_bf16_f32 v0, v0, v1
	v_cvt_pk_bf16_f32 v1, v2, v3
	v_cvt_pk_bf16_f32 v2, v4, v5
	v_cvt_pk_bf16_f32 v3, v6, v7
	s_waitcnt lgkmcnt(14)
	s_nop 0
	v_mfma_f32_32x32x16_bf16 v[64:79], v[134:137], v[0:3], v[64:79]
	s_waitcnt lgkmcnt(12)
	v_mfma_f32_32x32x16_bf16 v[48:63], v[138:141], v[0:3], v[48:63]
	v_exp_f32_e32 v8, v8
	v_exp_f32_e32 v9, v9
	v_add_f32_e32 v37, v8, v37
	v_exp_f32_e32 v10, v10
	v_add_f32_e32 v37, v9, v37
	v_exp_f32_e32 v11, v11
	v_add_f32_e32 v37, v10, v37
	v_exp_f32_e32 v12, v12
	v_add_f32_e32 v37, v11, v37
	v_exp_f32_e32 v13, v13
	v_add_f32_e32 v37, v12, v37
	v_exp_f32_e32 v14, v14
	v_add_f32_e32 v37, v13, v37
	v_exp_f32_e32 v15, v15
	v_add_f32_e32 v37, v14, v37
	s_nop 0
	v_add_f32_e32 v37, v15, v37
	v_cvt_pk_bf16_f32 v8, v8, v9
	v_cvt_pk_bf16_f32 v9, v10, v11
	v_cvt_pk_bf16_f32 v10, v12, v13
	v_cvt_pk_bf16_f32 v11, v14, v15
	s_waitcnt lgkmcnt(10)
	s_nop 0
	v_mfma_f32_32x32x16_bf16 v[64:79], v[142:145], v[8:11], v[64:79]
	s_waitcnt lgkmcnt(8)
	v_mfma_f32_32x32x16_bf16 v[48:63], v[146:149], v[8:11], v[48:63]
	s_waitcnt vmcnt(0)
	s_waitcnt lgkmcnt(0)
	v_add_u32_e32 v252, s37, v195
	ds_write_b128 v252, v[96:99]
	s_xor_b32 s2, s36, 3
	s_mulk_i32 s2, 0x2400
	v_add_u32_e32 v252, s2, v195
	ds_write_b128 v252, v[100:103]
	s_sub_i32 s3, 0x2400, s37
	v_add_u32_e32 v252, s3, v156
	v_add_u32_e32 v253, v252, v157
	v_add_u32_e32 v252, v252, v158
	ds_read_b128 v[134:137], v253
	ds_read_b128 v[138:141], v253 offset:32
	ds_read_b128 v[142:145], v253 offset:64
	ds_read_b128 v[146:149], v253 offset:96
	ds_read_b128 v[38:41], v252
	ds_read_b128 v[42:45], v252 offset:32
	v_exp_f32_e32 v16, v16
	v_exp_f32_e32 v17, v17
	v_add_f32_e32 v37, v16, v37
	s_waitcnt lgkmcnt(5)
	v_mfma_f32_32x32x16_bf16 v[0:15], v[134:137], v[80:83], 0
	v_exp_f32_e32 v18, v18
	v_add_f32_e32 v37, v17, v37
	v_exp_f32_e32 v19, v19
	v_add_f32_e32 v37, v18, v37
	v_exp_f32_e32 v20, v20
	v_add_f32_e32 v37, v19, v37
	v_exp_f32_e32 v21, v21
	v_add_f32_e32 v37, v20, v37
	s_waitcnt lgkmcnt(4)
	v_mfma_f32_32x32x16_bf16 v[0:15], v[138:141], v[84:87], v[0:15]
	v_exp_f32_e32 v22, v22
	v_add_f32_e32 v37, v21, v37
	v_exp_f32_e32 v23, v23
	v_add_f32_e32 v37, v22, v37
	s_nop 0
	v_add_f32_e32 v37, v23, v37
	v_cvt_pk_bf16_f32 v16, v16, v17
	v_cvt_pk_bf16_f32 v17, v18, v19
	v_cvt_pk_bf16_f32 v18, v20, v21
	v_cvt_pk_bf16_f32 v19, v22, v23
	s_nop 1
	v_mfma_f32_32x32x16_bf16 v[64:79], v[236:239], v[16:19], v[64:79]
	v_mfma_f32_32x32x16_bf16 v[48:63], v[240:243], v[16:19], v[48:63]
	ds_read_b128 v[96:99], v252 offset:64
	ds_read_b128 v[100:103], v252 offset:96
	v_exp_f32_e32 v24, v24
	v_exp_f32_e32 v25, v25
	v_add_f32_e32 v37, v24, v37
	s_waitcnt lgkmcnt(5)
	v_mfma_f32_32x32x16_bf16 v[0:15], v[142:145], v[88:91], v[0:15]
	v_exp_f32_e32 v26, v26
	v_add_f32_e32 v37, v25, v37
	v_exp_f32_e32 v27, v27
	v_add_f32_e32 v37, v26, v37
	v_exp_f32_e32 v28, v28
	v_add_f32_e32 v37, v27, v37
	v_exp_f32_e32 v29, v29
	v_add_f32_e32 v37, v28, v37
	s_waitcnt lgkmcnt(4)
	v_mfma_f32_32x32x16_bf16 v[0:15], v[146:149], v[92:95], v[0:15]
	v_exp_f32_e32 v30, v30
	v_add_f32_e32 v37, v29, v37
	v_exp_f32_e32 v31, v31
	v_add_f32_e32 v37, v30, v37
	s_nop 0
	v_add_f32_e32 v37, v31, v37
	v_cvt_pk_bf16_f32 v24, v24, v25
	v_cvt_pk_bf16_f32 v25, v26, v27
	v_cvt_pk_bf16_f32 v26, v28, v29
	v_cvt_pk_bf16_f32 v27, v30, v31
	s_nop 1
	v_mfma_f32_32x32x16_bf16 v[64:79], v[244:247], v[24:27], v[64:79]
	v_mfma_f32_32x32x16_bf16 v[48:63], v[248:251], v[24:27], v[48:63]
	s_waitcnt lgkmcnt(3)
	v_mfma_f32_32x32x16_bf16 v[16:31], v[38:41], v[80:83], 0
	s_waitcnt lgkmcnt(2)
	v_mfma_f32_32x32x16_bf16 v[16:31], v[42:45], v[84:87], v[16:31]
	v_fmac_f32_e32 v37, v121, v34
	v_mov_b32_e32 v123, v33
	v_mov_b32_e32 v121, v37
	s_waitcnt lgkmcnt(1)
	v_mfma_f32_32x32x16_bf16 v[16:31], v[96:99], v[88:91], v[16:31]
	s_waitcnt lgkmcnt(0)
	v_mfma_f32_32x32x16_bf16 v[16:31], v[100:103], v[92:95], v[16:31]
	s_branch .LBB0_1470
